# P1 in_proj K-loop restructured into 4 double phases per k-tile pair (32-MFMA bursts, half the barriers, ds_reads retired before each barrier; same DMA order; no SGPR base rewritten right after its DMA
# speedup vs baseline: 1.0140x; 1.0140x over previous
.LBB0_181:
	ds_read_b128 v[144:147], v157
	ds_read_b128 v[148:151], v157 offset:1024
	ds_read_b128 v[162:165], v157 offset:2048
	ds_read_b128 v[166:169], v157 offset:3072
	s_add_u32 s30, s28, 0xfff80080
	s_addc_u32 s31, s29, -1
	s_cmp_eq_u32 s54, 28
	s_cselect_b32 s35, s2, s31
	s_cselect_b32 s34, s3, s30
	s_cselect_b32 s31, s7, s27
	s_cselect_b32 s30, s9, s11
	s_add_i32 m0, s39, 0xc000
	ds_read_b128 v[170:173], v158
	ds_read_b128 v[174:177], v158 offset:1024
	ds_read_b128 v[178:181], v158 offset:2048
	ds_read_b128 v[186:189], v158 offset:3072
	ds_read_b128 v[194:197], v158 offset:4096
	ds_read_b128 v[198:201], v158 offset:5120
	ds_read_b128 v[202:205], v158 offset:6144
	ds_read_b128 v[206:209], v158 offset:7168
	global_load_lds_dwordx4 v136, s[28:29]
	s_add_i32 m0, s39, 0xe000
	s_nop 0
	global_load_lds_dwordx4 v138, s[28:29]
	ds_read_b128 v[210:213], v159
	ds_read_b128 v[214:217], v159 offset:1024
	ds_read_b128 v[218:221], v159 offset:2048
	ds_read_b128 v[222:225], v159 offset:3072
	s_waitcnt lgkmcnt(0)
	s_barrier
	s_setprio 1
	v_mfma_f32_16x16x32_bf16 v[124:127], v[144:147], v[170:173], v[124:127]
	v_mfma_f32_16x16x32_bf16 v[120:123], v[162:165], v[170:173], v[120:123]
	v_mfma_f32_16x16x32_bf16 v[108:111], v[144:147], v[178:181], v[108:111]
	v_mfma_f32_16x16x32_bf16 v[104:107], v[162:165], v[178:181], v[104:107]
	v_mfma_f32_16x16x32_bf16 v[92:95], v[144:147], v[194:197], v[92:95]
	v_mfma_f32_16x16x32_bf16 v[88:91], v[162:165], v[194:197], v[88:91]
	v_mfma_f32_16x16x32_bf16 v[76:79], v[144:147], v[202:205], v[76:79]
	v_mfma_f32_16x16x32_bf16 v[72:75], v[162:165], v[202:205], v[72:75]
	v_mfma_f32_16x16x32_bf16 v[124:127], v[148:151], v[174:177], v[124:127]
	v_mfma_f32_16x16x32_bf16 v[120:123], v[166:169], v[174:177], v[120:123]
	v_mfma_f32_16x16x32_bf16 v[108:111], v[148:151], v[186:189], v[108:111]
	v_mfma_f32_16x16x32_bf16 v[104:107], v[166:169], v[186:189], v[104:107]
	v_mfma_f32_16x16x32_bf16 v[92:95], v[148:151], v[198:201], v[92:95]
	v_mfma_f32_16x16x32_bf16 v[88:91], v[166:169], v[198:201], v[88:91]
	v_mfma_f32_16x16x32_bf16 v[76:79], v[148:151], v[206:209], v[76:79]
	v_mfma_f32_16x16x32_bf16 v[72:75], v[166:169], v[206:209], v[72:75]
	v_mfma_f32_16x16x32_bf16 v[116:119], v[210:213], v[170:173], v[116:119]
	v_mfma_f32_16x16x32_bf16 v[112:115], v[218:221], v[170:173], v[112:115]
	v_mfma_f32_16x16x32_bf16 v[100:103], v[210:213], v[178:181], v[100:103]
	v_mfma_f32_16x16x32_bf16 v[96:99], v[218:221], v[178:181], v[96:99]
	v_mfma_f32_16x16x32_bf16 v[84:87], v[210:213], v[194:197], v[84:87]
	v_mfma_f32_16x16x32_bf16 v[80:83], v[218:221], v[194:197], v[80:83]
	v_mfma_f32_16x16x32_bf16 v[68:71], v[210:213], v[202:205], v[68:71]
	v_mfma_f32_16x16x32_bf16 v[64:67], v[218:221], v[202:205], v[64:67]
	v_mfma_f32_16x16x32_bf16 v[116:119], v[214:217], v[174:177], v[116:119]
	v_mfma_f32_16x16x32_bf16 v[112:115], v[222:225], v[174:177], v[112:115]
	v_mfma_f32_16x16x32_bf16 v[100:103], v[214:217], v[186:189], v[100:103]
	v_mfma_f32_16x16x32_bf16 v[96:99], v[222:225], v[186:189], v[96:99]
	v_mfma_f32_16x16x32_bf16 v[84:87], v[214:217], v[198:201], v[84:87]
	v_mfma_f32_16x16x32_bf16 v[80:83], v[222:225], v[198:201], v[80:83]
	v_mfma_f32_16x16x32_bf16 v[68:71], v[214:217], v[206:209], v[68:71]
	v_mfma_f32_16x16x32_bf16 v[64:67], v[222:225], v[206:209], v[64:67]
	s_setprio 0
	s_barrier
	s_add_i32 s55, s48, s38
	s_add_u32 s58, s30, s0
	s_addc_u32 s59, s31, s1
	s_mov_b32 m0, s55
	s_nop 0
	global_load_lds_dwordx4 v130, s[30:31]
	s_add_i32 m0, s55, 0x2000
	s_nop 0
	global_load_lds_dwordx4 v134, s[30:31]
	s_mov_b32 m0, s39
	s_add_u32 s60, s34, s0
	s_addc_u32 s61, s35, s1
	ds_read_b128 v[170:173], v158 offset:16384
	ds_read_b128 v[174:177], v158 offset:17408
	ds_read_b128 v[178:181], v158 offset:18432
	ds_read_b128 v[186:189], v158 offset:19456
	ds_read_b128 v[194:197], v158 offset:20480
	ds_read_b128 v[198:201], v158 offset:21504
	ds_read_b128 v[202:205], v158 offset:22528
	ds_read_b128 v[206:209], v158 offset:23552
	global_load_lds_dwordx4 v128, s[34:35]
	s_mov_b32 m0, s40
	s_nop 0
	global_load_lds_dwordx4 v132, s[34:35]
	s_add_u32 s56, s30, 0x80000
	s_addc_u32 s57, s31, 0
	s_add_i32 s55, s49, s38
	s_mov_b32 m0, s55
	s_nop 0
	global_load_lds_dwordx4 v130, s[56:57]
	s_add_i32 m0, s55, 0x2000
	s_nop 0
	global_load_lds_dwordx4 v134, s[56:57]
	s_waitcnt vmcnt(6)
	s_waitcnt lgkmcnt(0)
	s_barrier
	s_setprio 1
	v_mfma_f32_16x16x32_bf16 v[60:63], v[144:147], v[170:173], v[60:63]
	v_mfma_f32_16x16x32_bf16 v[56:59], v[162:165], v[170:173], v[56:59]
	v_mfma_f32_16x16x32_bf16 v[44:47], v[144:147], v[178:181], v[44:47]
	v_mfma_f32_16x16x32_bf16 v[40:43], v[162:165], v[178:181], v[40:43]
	v_mfma_f32_16x16x32_bf16 v[28:31], v[144:147], v[194:197], v[28:31]
	v_mfma_f32_16x16x32_bf16 v[24:27], v[162:165], v[194:197], v[24:27]
	v_mfma_f32_16x16x32_bf16 v[12:15], v[144:147], v[202:205], v[12:15]
	v_mfma_f32_16x16x32_bf16 v[8:11], v[162:165], v[202:205], v[8:11]
	v_mfma_f32_16x16x32_bf16 v[60:63], v[148:151], v[174:177], v[60:63]
	v_mfma_f32_16x16x32_bf16 v[56:59], v[166:169], v[174:177], v[56:59]
	v_mfma_f32_16x16x32_bf16 v[44:47], v[148:151], v[186:189], v[44:47]
	v_mfma_f32_16x16x32_bf16 v[40:43], v[166:169], v[186:189], v[40:43]
	v_mfma_f32_16x16x32_bf16 v[28:31], v[148:151], v[198:201], v[28:31]
	v_mfma_f32_16x16x32_bf16 v[24:27], v[166:169], v[198:201], v[24:27]
	v_mfma_f32_16x16x32_bf16 v[12:15], v[148:151], v[206:209], v[12:15]
	v_mfma_f32_16x16x32_bf16 v[8:11], v[166:169], v[206:209], v[8:11]
	v_mfma_f32_16x16x32_bf16 v[52:55], v[210:213], v[170:173], v[52:55]
	v_mfma_f32_16x16x32_bf16 v[48:51], v[218:221], v[170:173], v[48:51]
	v_mfma_f32_16x16x32_bf16 v[36:39], v[210:213], v[178:181], v[36:39]
	v_mfma_f32_16x16x32_bf16 v[32:35], v[218:221], v[178:181], v[32:35]
	v_mfma_f32_16x16x32_bf16 v[20:23], v[210:213], v[194:197], v[20:23]
	v_mfma_f32_16x16x32_bf16 v[16:19], v[218:221], v[194:197], v[16:19]
	v_mfma_f32_16x16x32_bf16 v[4:7], v[210:213], v[202:205], v[4:7]
	v_mfma_f32_16x16x32_bf16 v[0:3], v[218:221], v[202:205], v[0:3]
	v_mfma_f32_16x16x32_bf16 v[52:55], v[214:217], v[174:177], v[52:55]
	v_mfma_f32_16x16x32_bf16 v[48:51], v[222:225], v[174:177], v[48:51]
	v_mfma_f32_16x16x32_bf16 v[36:39], v[214:217], v[186:189], v[36:39]
	v_mfma_f32_16x16x32_bf16 v[32:35], v[222:225], v[186:189], v[32:35]
	v_mfma_f32_16x16x32_bf16 v[20:23], v[214:217], v[198:201], v[20:23]
	v_mfma_f32_16x16x32_bf16 v[16:19], v[222:225], v[198:201], v[16:19]
	v_mfma_f32_16x16x32_bf16 v[4:7], v[214:217], v[206:209], v[4:7]
	v_mfma_f32_16x16x32_bf16 v[0:3], v[222:225], v[206:209], v[0:3]
	s_setprio 0
	s_add_i32 s55, 0, 0x18000
	v_add_u32_e32 v161, s55, v155
	s_barrier
	ds_read_b128 v[144:147], v161
	ds_read_b128 v[148:151], v161 offset:1024
	ds_read_b128 v[162:165], v161 offset:2048
	ds_read_b128 v[166:169], v161 offset:3072
	s_add_u32 s34, s34, 0x80000
	s_addc_u32 s35, s35, 0
	s_mov_b32 m0, s41
	ds_read_b128 v[170:173], v158 offset:32768
	ds_read_b128 v[174:177], v158 offset:33792
	ds_read_b128 v[178:181], v158 offset:34816
	ds_read_b128 v[186:189], v158 offset:35840
	ds_read_b128 v[194:197], v158 offset:36864
	ds_read_b128 v[198:201], v158 offset:37888
	ds_read_b128 v[202:205], v158 offset:38912
	ds_read_b128 v[206:209], v158 offset:39936
	global_load_lds_dwordx4 v128, s[34:35]
	s_mov_b32 m0, s42
	s_nop 0
	global_load_lds_dwordx4 v132, s[34:35]
	v_add_u32_e32 v161, 0x1c000, v155
	ds_read_b128 v[210:213], v161
	ds_read_b128 v[214:217], v161 offset:1024
	ds_read_b128 v[218:221], v161 offset:2048
	ds_read_b128 v[222:225], v161 offset:3072
	s_waitcnt lgkmcnt(0)
	s_barrier
	s_setprio 1
	v_mfma_f32_16x16x32_bf16 v[124:127], v[144:147], v[170:173], v[124:127]
	v_mfma_f32_16x16x32_bf16 v[120:123], v[162:165], v[170:173], v[120:123]
	v_mfma_f32_16x16x32_bf16 v[108:111], v[144:147], v[178:181], v[108:111]
	v_mfma_f32_16x16x32_bf16 v[104:107], v[162:165], v[178:181], v[104:107]
	v_mfma_f32_16x16x32_bf16 v[92:95], v[144:147], v[194:197], v[92:95]
	v_mfma_f32_16x16x32_bf16 v[88:91], v[162:165], v[194:197], v[88:91]
	v_mfma_f32_16x16x32_bf16 v[76:79], v[144:147], v[202:205], v[76:79]
	v_mfma_f32_16x16x32_bf16 v[72:75], v[162:165], v[202:205], v[72:75]
	v_mfma_f32_16x16x32_bf16 v[124:127], v[148:151], v[174:177], v[124:127]
	v_mfma_f32_16x16x32_bf16 v[120:123], v[166:169], v[174:177], v[120:123]
	v_mfma_f32_16x16x32_bf16 v[108:111], v[148:151], v[186:189], v[108:111]
	v_mfma_f32_16x16x32_bf16 v[104:107], v[166:169], v[186:189], v[104:107]
	v_mfma_f32_16x16x32_bf16 v[92:95], v[148:151], v[198:201], v[92:95]
	v_mfma_f32_16x16x32_bf16 v[88:91], v[166:169], v[198:201], v[88:91]
	v_mfma_f32_16x16x32_bf16 v[76:79], v[148:151], v[206:209], v[76:79]
	v_mfma_f32_16x16x32_bf16 v[72:75], v[166:169], v[206:209], v[72:75]
	v_mfma_f32_16x16x32_bf16 v[116:119], v[210:213], v[170:173], v[116:119]
	v_mfma_f32_16x16x32_bf16 v[112:115], v[218:221], v[170:173], v[112:115]
	v_mfma_f32_16x16x32_bf16 v[100:103], v[210:213], v[178:181], v[100:103]
	v_mfma_f32_16x16x32_bf16 v[96:99], v[218:221], v[178:181], v[96:99]
	v_mfma_f32_16x16x32_bf16 v[84:87], v[210:213], v[194:197], v[84:87]
	v_mfma_f32_16x16x32_bf16 v[80:83], v[218:221], v[194:197], v[80:83]
	v_mfma_f32_16x16x32_bf16 v[68:71], v[210:213], v[202:205], v[68:71]
	v_mfma_f32_16x16x32_bf16 v[64:67], v[218:221], v[202:205], v[64:67]
	v_mfma_f32_16x16x32_bf16 v[116:119], v[214:217], v[174:177], v[116:119]
	v_mfma_f32_16x16x32_bf16 v[112:115], v[222:225], v[174:177], v[112:115]
	v_mfma_f32_16x16x32_bf16 v[100:103], v[214:217], v[186:189], v[100:103]
	v_mfma_f32_16x16x32_bf16 v[96:99], v[222:225], v[186:189], v[96:99]
	v_mfma_f32_16x16x32_bf16 v[84:87], v[214:217], v[198:201], v[84:87]
	v_mfma_f32_16x16x32_bf16 v[80:83], v[222:225], v[198:201], v[80:83]
	v_mfma_f32_16x16x32_bf16 v[68:71], v[214:217], v[206:209], v[68:71]
	v_mfma_f32_16x16x32_bf16 v[64:67], v[222:225], v[206:209], v[64:67]
	s_setprio 0
	s_barrier
	s_add_i32 s34, 0, 0x1c000
	s_add_i32 s35, s55, s38
	s_mov_b32 m0, s35
	s_nop 0
	global_load_lds_dwordx4 v130, s[58:59]
	s_add_i32 m0, s35, 0x2000
	s_nop 0
	global_load_lds_dwordx4 v134, s[58:59]
	s_mov_b32 m0, s44
	ds_read_b128 v[170:173], v158 offset:49152
	ds_read_b128 v[174:177], v158 offset:50176
	ds_read_b128 v[178:181], v158 offset:51200
	ds_read_b128 v[186:189], v158 offset:52224
	ds_read_b128 v[194:197], v158 offset:53248
	ds_read_b128 v[198:201], v158 offset:54272
	ds_read_b128 v[202:205], v158 offset:55296
	ds_read_b128 v[206:209], v158 offset:56320
	global_load_lds_dwordx4 v128, s[60:61]
	s_mov_b32 m0, s45
	s_nop 0
	global_load_lds_dwordx4 v132, s[60:61]
	s_add_u32 s30, s30, 0x80080
	s_addc_u32 s31, s31, 0
	s_add_i32 s34, s34, s38
	s_mov_b32 m0, s34
	s_nop 0
	global_load_lds_dwordx4 v130, s[30:31]
	s_add_i32 m0, s34, 0x2000
	s_nop 0
	global_load_lds_dwordx4 v134, s[30:31]
	s_waitcnt vmcnt(6)
	s_waitcnt lgkmcnt(0)
	s_barrier
; __device__ __forceinline__ unsigned pk2(float lo, float hi) { unsigned r; asm("v_cvt_pk_bf16_f32 %0, %1, %2" : "=v"(r) : "v"(lo), "v"(hi)); return r; }
; template <class Epi>
; __device__ __forceinline__ void gemm_phase(LAS unsigned char* lds, const GemmD g, const Epi& E) {
;     ...
;         for (int t = 0; t < nt; t += 2) PG8_KITER(t);
;     __device__ __forceinline__ void operator()(const f32x4 (&acc)[2][2][4][2], const Unit& u, int wr, int wc, int fr, int fq) const {
;         const int row0 = u.pm * BM + wr * 64 + fr, col0 = u.pn * BM + wc * 32 + 8 * fq;
;         const bool sig = (u.pn >= 36 && u.pn < 52), isdt = (u.pn == 52);
; #pragma unroll
;         for (int ai = 0; ai < 2; ++ai)
; #pragma unroll
;             for (int m = 0; m < 4; ++m) { const int row = row0 + ai * HALF + m * 16;
; #pragma unroll
;                 for (int bj = 0; bj < 2; ++bj) { const f32x4 v0 = acc[ai][bj][m][0], v1 = acc[ai][bj][m][1]; const int col = col0 + bj * HALF;
;                     if (sig) {
;                         const int c = (col - C_GS) >> 1;
;                         float ra[4], gp[4];
; #pragma unroll
;                         for (int j = 0; j < 4; ++j) { const float ea = __expf(-fminf(fmaxf(v0[j], -30.f), 30.f)), eb = __expf(-fminf(fmaxf(v1[j], -30.f), 30.f)); gp[j] = __builtin_amdgcn_rcpf(1.0f + eb); ra[j] = (1.0f + eb) * __builtin_amdgcn_rcpf(1.0f + ea); }
;                         u32x2 wr_, wg; wr_.x = pk2(ra[0], ra[1]); wr_.y = pk2(ra[2], ra[3]); wg.x = pk2(gp[0], gp[1]); wg.y = pk2(gp[2], gp[3]);
;                         *(u32x2*)(proj + (size_t)row * NPROJ + C_GS + c) = wr_;
;                         *(u32x2*)(proj + (size_t)row * NPROJ + C_GP + c) = wg;
;                     } else {
;                         u32x4 w; w.x = pk2(v0[0], v0[1]); w.y = pk2(v0[2], v0[3]); w.z = pk2(v1[0], v1[1]); w.w = pk2(v1[2], v1[3]);
;                         *(u32x4*)(proj + (size_t)row * NPROJ + col) = w;
;                         if (isdt && col < C_DT + 32) { float* d = dtraw + (size_t)row * 32 + (col - C_DT); *(f32x4*)d = v0; *(f32x4*)(d + 4) = v1; } } } }
	s_setprio 1
	v_mfma_f32_16x16x32_bf16 v[60:63], v[144:147], v[170:173], v[60:63]
	v_mfma_f32_16x16x32_bf16 v[56:59], v[162:165], v[170:173], v[56:59]
	v_mfma_f32_16x16x32_bf16 v[44:47], v[144:147], v[178:181], v[44:47]
	v_mfma_f32_16x16x32_bf16 v[40:43], v[162:165], v[178:181], v[40:43]
	v_mfma_f32_16x16x32_bf16 v[28:31], v[144:147], v[194:197], v[28:31]
	v_mfma_f32_16x16x32_bf16 v[24:27], v[162:165], v[194:197], v[24:27]
	v_mfma_f32_16x16x32_bf16 v[12:15], v[144:147], v[202:205], v[12:15]
	v_mfma_f32_16x16x32_bf16 v[8:11], v[162:165], v[202:205], v[8:11]
	v_mfma_f32_16x16x32_bf16 v[60:63], v[148:151], v[174:177], v[60:63]
	v_mfma_f32_16x16x32_bf16 v[56:59], v[166:169], v[174:177], v[56:59]
	v_mfma_f32_16x16x32_bf16 v[44:47], v[148:151], v[186:189], v[44:47]
	v_mfma_f32_16x16x32_bf16 v[40:43], v[166:169], v[186:189], v[40:43]
	v_mfma_f32_16x16x32_bf16 v[28:31], v[148:151], v[198:201], v[28:31]
	v_mfma_f32_16x16x32_bf16 v[24:27], v[166:169], v[198:201], v[24:27]
	v_mfma_f32_16x16x32_bf16 v[12:15], v[148:151], v[206:209], v[12:15]
	v_mfma_f32_16x16x32_bf16 v[8:11], v[166:169], v[206:209], v[8:11]
	v_mfma_f32_16x16x32_bf16 v[52:55], v[210:213], v[170:173], v[52:55]
	v_mfma_f32_16x16x32_bf16 v[48:51], v[218:221], v[170:173], v[48:51]
	v_mfma_f32_16x16x32_bf16 v[36:39], v[210:213], v[178:181], v[36:39]
	v_mfma_f32_16x16x32_bf16 v[32:35], v[218:221], v[178:181], v[32:35]
	v_mfma_f32_16x16x32_bf16 v[20:23], v[210:213], v[194:197], v[20:23]
	v_mfma_f32_16x16x32_bf16 v[16:19], v[218:221], v[194:197], v[16:19]
	v_mfma_f32_16x16x32_bf16 v[4:7], v[210:213], v[202:205], v[4:7]
	v_mfma_f32_16x16x32_bf16 v[0:3], v[218:221], v[202:205], v[0:3]
	v_mfma_f32_16x16x32_bf16 v[52:55], v[214:217], v[174:177], v[52:55]
	v_mfma_f32_16x16x32_bf16 v[48:51], v[222:225], v[174:177], v[48:51]
	v_mfma_f32_16x16x32_bf16 v[36:39], v[214:217], v[186:189], v[36:39]
	v_mfma_f32_16x16x32_bf16 v[32:35], v[222:225], v[186:189], v[32:35]
	v_mfma_f32_16x16x32_bf16 v[20:23], v[214:217], v[198:201], v[20:23]
	v_mfma_f32_16x16x32_bf16 v[16:19], v[222:225], v[198:201], v[16:19]
	v_mfma_f32_16x16x32_bf16 v[4:7], v[214:217], v[206:209], v[4:7]
	v_mfma_f32_16x16x32_bf16 v[0:3], v[222:225], v[206:209], v[0:3]
	s_setprio 0
	s_add_i32 s54, s54, 2
	s_add_u32 s28, s28, 0x100
	s_addc_u32 s29, s29, 0
	s_add_u32 s11, s11, 0x100
	s_addc_u32 s27, s27, 0
	s_cmp_gt_u32 s54, 29
	s_barrier
	s_cbranch_scc0 .LBB0_181
	s_sub_i32 s2, s6, 36
	v_lshl_add_u32 v146, s26, 8, v154
	s_cmp_gt_u32 s2, 15
	s_cselect_b64 s[28:29], -1, 0
	s_cmp_eq_u32 s6, 52
	v_ashrrev_i32_e32 v147, 31, v146
	v_mad_i64_i32 v[152:153], s[2:3], v146, s50, 0
	v_lshl_or_b32 v144, s6, 8, v156
	s_cselect_b64 s[26:27], -1, 0
	v_lshlrev_b64 v[150:151], 7, v[146:147]
	s_mov_b64 s[2:3], -1
	s_and_b64 vcc, exec, s[28:29]
	s_cbranch_vccz .LBB0_186
	v_lshl_add_u64 v[148:149], s[92:93], 0, v[152:153]
	v_ashrrev_i32_e32 v145, 31, v144
	v_cmp_gt_i32_e32 vcc, s52, v144
	v_lshl_add_u64 v[148:149], v[144:145], 1, v[148:149]
	s_and_b64 s[2:3], s[26:27], vcc
	v_cvt_pk_bf16_f32 v162, v124, v125
	v_cvt_pk_bf16_f32 v163, v126, v127
	v_cvt_pk_bf16_f32 v164, v120, v121
	v_cvt_pk_bf16_f32 v165, v122, v123
	global_store_dwordx4 v[148:149], v[162:165], off
	s_and_saveexec_b64 s[6:7], s[2:3]
	s_cbranch_execz .LBB0_185
	v_lshl_add_u64 v[148:149], s[14:15], 0, v[150:151]
	v_lshl_add_u64 v[148:149], v[144:145], 2, v[148:149]
	v_add_co_u32_e32 v162, vcc, 0xffff3000, v148
	s_nop 1
	v_addc_co_u32_e32 v163, vcc, -1, v149, vcc
	v_add_co_u32_e32 v148, vcc, 0xffff4000, v148
	global_store_dwordx4 v[162:163], v[124:127], off
	s_nop 0
	v_addc_co_u32_e32 v149, vcc, -1, v149, vcc
	global_store_dwordx4 v[148:149], v[120:123], off offset:-4080
